# table item: second wait relaxed to vmcnt(41) so the table loads overlap the range-reduction arithmetic
# speedup vs baseline: 1.0068x; 1.0042x over previous
; __device__ __forceinline__ void prologue(const Args& a, LAS unsigned char* lds, int tid, int wave, int lane) {
;     ...
;         const int l = i / (NG * NP), g = (i / NP) % NG, p = i % NP;
;         const float lre = a.in[I_LRE][i], lim = a.in[I_LIM][i], step = expf(a.in[I_LSTEP][l * NG + g]);
;         const float mag = expf(lre * step), ar = mag * cosf(lim * step), ai = mag * sinf(lim * step), den = lre * lre + lim * lim;
.LBB0_142:
	v_ashrrev_i32_e32 v1, 31, v0
	v_lshrrev_b32_e32 v5, 26, v1
	v_add_u32_e32 v5, v0, v5
	v_ashrrev_i32_e32 v17, 6, v5
	v_lshrrev_b32_e32 v5, 27, v17
	v_lshrrev_b32_e32 v2, 21, v1
	v_add_u32_e32 v5, v17, v5
	v_add_u32_e32 v2, v0, v2
	v_and_b32_e32 v5, 0xffffffe0, v5
	v_ashrrev_i32_e32 v2, 11, v2
	v_sub_u32_e32 v5, v17, v5
	v_lshl_add_u32 v6, v2, 5, v5
	v_ashrrev_i32_e32 v7, 31, v6
	v_lshl_add_u64 v[18:19], v[6:7], 2, s[84:85]
	global_load_dword v2, v[18:19], off
	s_waitcnt vmcnt(3)
	v_lshlrev_b64 v[20:21], 2, v[0:1]
	v_lshl_add_u64 v[18:19], s[82:83], 0, v[20:21]
	global_load_dword v18, v[18:19], off
	v_lshl_add_u64 v[20:21], s[80:81], 0, v[20:21]
	global_load_dword v19, v[20:21], off
	v_readlane_b32 s98, v252, 16
	v_readlane_b32 s99, v252, 17
	v_readlane_b32 s100, v252, 20
	v_readlane_b32 s101, v252, 21
	v_lshlrev_b32_e32 v136, 6, v0
	v_mov_b32_e32 v137, 0
	v_lshl_add_u64 v[138:139], s[98:99], 0, v[136:137]
	v_lshl_add_u64 v[140:141], s[86:87], 0, v[136:137]
	v_readlane_b32 s98, v252, 18
	v_readlane_b32 s99, v252, 19
	global_load_dwordx4 v[104:107], v[138:139], off
	global_load_dwordx4 v[108:111], v[138:139], off offset:16
	global_load_dwordx4 v[112:115], v[138:139], off offset:32
	global_load_dwordx4 v[116:119], v[138:139], off offset:48
	global_load_dwordx4 v[120:123], v[140:141], off
	global_load_dwordx4 v[124:127], v[140:141], off offset:16
	global_load_dwordx4 v[128:131], v[140:141], off offset:32
	global_load_dwordx4 v[132:135], v[140:141], off offset:48
	v_lshlrev_b32_e32 v136, 12, v17
	v_and_b32_e32 v138, 63, v0
	v_lshl_add_u32 v136, v138, 2, v136
	v_lshl_add_u64 v[138:139], s[98:99], 0, v[136:137]
	v_lshl_add_u64 v[140:141], s[100:101], 0, v[136:137]
	global_load_dword v64, v[140:141], off
	global_load_dword v142, v[138:139], off
	global_load_dword v65, v[140:141], off offset:256
	global_load_dword v143, v[138:139], off offset:256
	global_load_dword v66, v[140:141], off offset:512
	global_load_dword v144, v[138:139], off offset:512
	global_load_dword v67, v[140:141], off offset:768
	global_load_dword v145, v[138:139], off offset:768
	global_load_dword v68, v[140:141], off offset:1024
	global_load_dword v146, v[138:139], off offset:1024
	global_load_dword v69, v[140:141], off offset:1280
	global_load_dword v147, v[138:139], off offset:1280
	global_load_dword v70, v[140:141], off offset:1536
	global_load_dword v148, v[138:139], off offset:1536
	global_load_dword v71, v[140:141], off offset:1792
	global_load_dword v149, v[138:139], off offset:1792
	global_load_dword v72, v[140:141], off offset:2048
	global_load_dword v150, v[138:139], off offset:2048
	global_load_dword v73, v[140:141], off offset:2304
	global_load_dword v151, v[138:139], off offset:2304
	global_load_dword v74, v[140:141], off offset:2560
	global_load_dword v152, v[138:139], off offset:2560
	global_load_dword v75, v[140:141], off offset:2816
	global_load_dword v153, v[138:139], off offset:2816
	global_load_dword v76, v[140:141], off offset:3072
	global_load_dword v154, v[138:139], off offset:3072
	global_load_dword v77, v[140:141], off offset:3328
	global_load_dword v155, v[138:139], off offset:3328
	global_load_dword v78, v[140:141], off offset:3584
	global_load_dword v156, v[138:139], off offset:3584
	global_load_dword v79, v[140:141], off offset:3840
	global_load_dword v157, v[138:139], off offset:3840
	s_waitcnt vmcnt(42)
	v_mul_f32_e32 v5, 0x3fb8aa3b, v2
	v_fma_f32 v20, v2, s24, -v5
	v_rndne_f32_e32 v21, v5
	v_fmac_f32_e32 v20, 0x32a5705f, v2
	v_sub_f32_e32 v5, v5, v21
	v_add_f32_e32 v5, v5, v20
	v_cvt_i32_f32_e32 v21, v21
	v_exp_f32_e32 v5, v5
	v_cmp_ngt_f32_e32 vcc, s25, v2
	v_ldexp_f32 v5, v5, v21
	s_nop 0
	v_cndmask_b32_e32 v5, 0, v5, vcc
	v_cmp_nlt_f32_e32 vcc, s26, v2
	s_nop 1
	v_cndmask_b32_e32 v21, v11, v5, vcc
	s_waitcnt vmcnt(41)
	v_mul_f32_e32 v5, v18, v21
	v_and_b32_e32 v20, 0x7fffffff, v5
	v_lshrrev_b32_e32 v2, 23, v20
	v_and_b32_e32 v22, 0x7fffff, v20
	v_cmp_nlt_f32_e64 s[18:19], |v5|, s27
	v_add_u32_e32 v25, 0xffffff88, v2
	v_or_b32_e32 v24, 0x800000, v22
	s_and_saveexec_b64 s[0:1], s[18:19]
	s_xor_b64 s[20:21], exec, s[0:1]
	s_cbranch_execz .LBB0_144
	v_cmp_lt_u32_e32 vcc, 63, v25
	s_nop 1
	v_cndmask_b32_e32 v2, 0, v14, vcc
	v_add_u32_e32 v2, v2, v25
	v_cmp_lt_u32_e64 s[0:1], 31, v2
	s_nop 1
	v_cndmask_b32_e64 v22, 0, v15, s[0:1]
	v_add_u32_e32 v2, v22, v2
	v_cmp_lt_u32_e64 s[4:5], 31, v2
	s_nop 1
	v_cndmask_b32_e64 v22, 0, v15, s[4:5]
	v_add_u32_e32 v38, v22, v2
	v_mad_u64_u32 v[22:23], s[6:7], v24, s28, 0
	v_mov_b32_e32 v2, v23
	v_mad_u64_u32 v[26:27], s[6:7], v24, s29, v[2:3]
	v_mov_b32_e32 v2, v27
	v_mad_u64_u32 v[28:29], s[6:7], v24, s33, v[2:3]
	v_mov_b32_e32 v2, v29
	v_mad_u64_u32 v[30:31], s[6:7], v24, s54, v[2:3]
	v_mov_b32_e32 v2, v31
	v_mad_u64_u32 v[32:33], s[6:7], v24, s55, v[2:3]
	v_mov_b32_e32 v2, v33
	v_mad_u64_u32 v[34:35], s[6:7], v24, s56, v[2:3]
	v_mov_b32_e32 v2, v35
	v_mad_u64_u32 v[36:37], s[6:7], v24, s57, v[2:3]
	v_cndmask_b32_e32 v23, v34, v30, vcc
	v_cndmask_b32_e32 v2, v36, v32, vcc
	v_cndmask_b32_e32 v29, v37, v34, vcc
	v_cndmask_b32_e64 v27, v2, v23, s[0:1]
	v_cndmask_b32_e64 v2, v29, v2, s[0:1]
	v_cndmask_b32_e32 v29, v32, v28, vcc
	v_cndmask_b32_e64 v23, v23, v29, s[0:1]
	v_cndmask_b32_e32 v26, v30, v26, vcc
	v_cndmask_b32_e64 v2, v2, v27, s[4:5]
	v_cndmask_b32_e64 v27, v27, v23, s[4:5]
	v_sub_u32_e32 v31, 32, v38
	v_cndmask_b32_e64 v29, v29, v26, s[0:1]
	v_alignbit_b32 v32, v2, v27, v31
	v_cmp_eq_u32_e64 s[6:7], 0, v38
	v_cndmask_b32_e64 v23, v23, v29, s[4:5]
	v_cndmask_b32_e32 v22, v28, v22, vcc
	v_cndmask_b32_e64 v2, v32, v2, s[6:7]
	v_alignbit_b32 v30, v27, v23, v31
	v_cndmask_b32_e64 v22, v26, v22, s[0:1]
	v_cndmask_b32_e64 v27, v30, v27, s[6:7]
	v_bfe_u32 v33, v2, 29, 1
	v_cndmask_b32_e64 v22, v29, v22, s[4:5]
	v_alignbit_b32 v30, v2, v27, 30
	v_sub_u32_e32 v34, 0, v33
	v_alignbit_b32 v26, v23, v22, v31
	v_xor_b32_e32 v30, v30, v34
	v_cndmask_b32_e64 v23, v26, v23, s[6:7]
	v_alignbit_b32 v26, v27, v23, 30
	v_ffbh_u32_e32 v27, v30
	v_min_u32_e32 v27, 32, v27
	v_alignbit_b32 v22, v23, v22, 30
	v_xor_b32_e32 v26, v26, v34
	v_sub_u32_e32 v28, 31, v27
	v_xor_b32_e32 v22, v22, v34
	v_alignbit_b32 v29, v30, v26, v28
	v_alignbit_b32 v22, v26, v22, v28
	v_alignbit_b32 v23, v29, v22, 9
	v_ffbh_u32_e32 v26, v23
	v_min_u32_e32 v26, 32, v26
	v_lshrrev_b32_e32 v32, 29, v2
	v_not_b32_e32 v28, v26
	v_alignbit_b32 v22, v23, v22, v28
	v_lshlrev_b32_e32 v23, 31, v32
	v_or_b32_e32 v28, 0x33000000, v23
	v_add_lshl_u32 v26, v26, v27, 23
	v_lshrrev_b32_e32 v22, 9, v22
	v_sub_u32_e32 v26, v28, v26
	v_or_b32_e32 v23, 0.5, v23
	v_lshlrev_b32_e32 v27, 23, v27
	v_or_b32_e32 v22, v26, v22
	v_lshrrev_b32_e32 v26, 9, v29
	v_sub_u32_e32 v23, v23, v27
	v_or_b32_e32 v23, v26, v23
	v_mul_f32_e32 v26, 0x3fc90fda, v23
	v_fma_f32 v27, v23, s60, -v26
	v_fmac_f32_e32 v27, 0x33a22168, v23
	v_fmac_f32_e32 v27, 0x3fc90fda, v22
	v_lshrrev_b32_e32 v2, 30, v2
	v_add_f32_e32 v23, v26, v27
	v_add_u32_e32 v22, v33, v2
